# G1 items remapped so each XCC owns one batch: seams P1-G1 and G1-G2 become XCC-local barriers; seam 0 rewritten (census included)
# speedup vs baseline: 1.0411x; 1.0092x over previous
_Z10fwd_kernel4Args:
	s_load_dwordx8 s[68:75], s[0:1], 0x80
	s_load_dword s96, s[0:1], 0xb8
	s_load_dwordx4 s[92:95], s[0:1], 0xa0
	s_load_dwordx2 s[22:23], s[0:1], 0xb0
	s_add_u32 s6, s0, 0xb0
	v_and_b32_e32 v1, 0x3ff, v0
	s_addc_u32 s7, s1, 0
	v_cmp_gt_u32_e32 vcc, 2, v1
	s_and_saveexec_b64 s[4:5], vcc
	v_lshl_add_u32 v2, v1, 2, 0
	v_add_u32_e32 v2, 0x23fc0, v2
	v_mov_b32_e32 v3, 0
	ds_write_b32 v2, v3
	s_or_b64 exec, exec, s[4:5]
	s_waitcnt lgkmcnt(0)
	s_barrier
	s_mov_b32 s3, 0
	v_writelane_b32 v244, s3, 42
	s_mov_b32 s3, 0
	v_writelane_b32 v244, s3, 43
	v_writelane_b32 v244, s22, 41
	v_writelane_b32 v244, s2, 44
	s_getreg_b32 s3, hwreg(HW_REG_XCC_ID, 0, 4)
	s_and_b32 s33, s3, 15
	v_cmp_eq_u32_e32 vcc, 0, v1
	s_and_saveexec_b64 s[4:5], vcc
	s_cbranch_execz .LBB0_5
	s_mov_b64 s[8:9], exec
	v_mbcnt_lo_u32_b32 v2, s8, 0
	v_mbcnt_hi_u32_b32 v2, s9, v2
	v_cmp_eq_u32_e32 vcc, 0, v2
	s_and_b64 s[10:11], exec, vcc
	s_mov_b64 exec, s[10:11]
	s_cbranch_execz .LBB0_5
	s_lshl_b32 s3, s33, 8
	s_bcnt1_i32_b64 s8, s[8:9]
	v_mov_b32_e32 v2, s3
	v_mov_b32_e32 v3, s8
	global_atomic_add v2, v3, s[92:93] offset:1024

.LBB0_95:
	s_cmp_gt_i32 s95, 1
	s_cselect_b64 s[0:1], -1, 0
	s_and_b64 s[4:5], s[18:19], s[0:1]
	s_andn2_b64 vcc, exec, s[4:5]
	s_cbranch_vccnz .LBB0_151
	s_waitcnt vmcnt(0)
	s_cmp_gt_u32 s14, 63
	s_waitcnt lgkmcnt(0)
	s_barrier
	s_cbranch_scc1 .LBB0_150
	v_mbcnt_hi_u32_b32 v0, -1, v192
	v_cmp_eq_u32_e32 vcc, 0, v0
	s_and_saveexec_b64 s[4:5], vcc
	s_cbranch_execz .LBB0_149
	s_waitcnt vmcnt(0) lgkmcnt(0)
	v_mov_b32_e32 v1, 1
	s_getreg_b32 s10, hwreg(HW_REG_XCC_ID, 0, 4)
	s_and_b32 s10, s10, 15
	v_mov_b32_e32 v0, 0x400
	s_mov_b32 s11, 0
.Lxb0_cen:
	global_load_dword v2, v0, s[92:93] sc1
	global_load_dword v3, v0, s[92:93] offset:256 sc1
	global_load_dword v4, v0, s[92:93] offset:512 sc1
	global_load_dword v5, v0, s[92:93] offset:768 sc1
	global_load_dword v6, v0, s[92:93] offset:1024 sc1
	global_load_dword v7, v0, s[92:93] offset:1280 sc1
	global_load_dword v8, v0, s[92:93] offset:1536 sc1
	global_load_dword v9, v0, s[92:93] offset:1792 sc1
	global_load_dword v10, v0, s[92:93] offset:2048 sc1
	global_load_dword v11, v0, s[92:93] offset:2304 sc1
	global_load_dword v12, v0, s[92:93] offset:2560 sc1
	global_load_dword v13, v0, s[92:93] offset:2816 sc1
	global_load_dword v14, v0, s[92:93] offset:3072 sc1
	global_load_dword v15, v0, s[92:93] offset:3328 sc1
	global_load_dword v16, v0, s[92:93] offset:3584 sc1
	global_load_dword v17, v0, s[92:93] offset:3840 sc1
	s_waitcnt vmcnt(0)
	s_mov_b32 s6, 0
	s_mov_b32 s7, 0
	s_mov_b32 s13, 0
	v_readfirstlane_b32 s12, v2
	s_add_u32 s6, s6, s12
	s_cmp_lg_u32 s12, 0
	s_addc_u32 s7, s7, 0
	s_cmp_eq_u32 s10, 0
	s_cselect_b32 s13, s12, s13
	v_readfirstlane_b32 s12, v3
	s_add_u32 s6, s6, s12
	s_cmp_lg_u32 s12, 0
	s_addc_u32 s7, s7, 0
	s_cmp_eq_u32 s10, 1
	s_cselect_b32 s13, s12, s13
	v_readfirstlane_b32 s12, v4
	s_add_u32 s6, s6, s12
	s_cmp_lg_u32 s12, 0
	s_addc_u32 s7, s7, 0
	s_cmp_eq_u32 s10, 2
	s_cselect_b32 s13, s12, s13
	v_readfirstlane_b32 s12, v5
	s_add_u32 s6, s6, s12
	s_cmp_lg_u32 s12, 0
	s_addc_u32 s7, s7, 0
	s_cmp_eq_u32 s10, 3
	s_cselect_b32 s13, s12, s13
	v_readfirstlane_b32 s12, v6
	s_add_u32 s6, s6, s12
	s_cmp_lg_u32 s12, 0
	s_addc_u32 s7, s7, 0
	s_cmp_eq_u32 s10, 4
	s_cselect_b32 s13, s12, s13
	v_readfirstlane_b32 s12, v7
	s_add_u32 s6, s6, s12
	s_cmp_lg_u32 s12, 0
	s_addc_u32 s7, s7, 0
	s_cmp_eq_u32 s10, 5
	s_cselect_b32 s13, s12, s13
	v_readfirstlane_b32 s12, v8
	s_add_u32 s6, s6, s12
	s_cmp_lg_u32 s12, 0
	s_addc_u32 s7, s7, 0
	s_cmp_eq_u32 s10, 6
	s_cselect_b32 s13, s12, s13
	v_readfirstlane_b32 s12, v9
	s_add_u32 s6, s6, s12
	s_cmp_lg_u32 s12, 0
	s_addc_u32 s7, s7, 0
	s_cmp_eq_u32 s10, 7
	s_cselect_b32 s13, s12, s13
	v_readfirstlane_b32 s12, v10
	s_add_u32 s6, s6, s12
	s_cmp_lg_u32 s12, 0
	s_addc_u32 s7, s7, 0
	s_cmp_eq_u32 s10, 8
	s_cselect_b32 s13, s12, s13
	v_readfirstlane_b32 s12, v11
	s_add_u32 s6, s6, s12
	s_cmp_lg_u32 s12, 0
	s_addc_u32 s7, s7, 0
	s_cmp_eq_u32 s10, 9
	s_cselect_b32 s13, s12, s13
	v_readfirstlane_b32 s12, v12
	s_add_u32 s6, s6, s12
	s_cmp_lg_u32 s12, 0
	s_addc_u32 s7, s7, 0
	s_cmp_eq_u32 s10, 10
	s_cselect_b32 s13, s12, s13
	v_readfirstlane_b32 s12, v13
	s_add_u32 s6, s6, s12
	s_cmp_lg_u32 s12, 0
	s_addc_u32 s7, s7, 0
	s_cmp_eq_u32 s10, 11
	s_cselect_b32 s13, s12, s13
	v_readfirstlane_b32 s12, v14
	s_add_u32 s6, s6, s12
	s_cmp_lg_u32 s12, 0
	s_addc_u32 s7, s7, 0
	s_cmp_eq_u32 s10, 12
	s_cselect_b32 s13, s12, s13
	v_readfirstlane_b32 s12, v15
	s_add_u32 s6, s6, s12
	s_cmp_lg_u32 s12, 0
	s_addc_u32 s7, s7, 0
	s_cmp_eq_u32 s10, 13
	s_cselect_b32 s13, s12, s13
	v_readfirstlane_b32 s12, v16
	s_add_u32 s6, s6, s12
	s_cmp_lg_u32 s12, 0
	s_addc_u32 s7, s7, 0
	s_cmp_eq_u32 s10, 14
	s_cselect_b32 s13, s12, s13
	v_readfirstlane_b32 s12, v17
	s_add_u32 s6, s6, s12
	s_cmp_lg_u32 s12, 0
	s_addc_u32 s7, s7, 0
	s_cmp_eq_u32 s10, 15
	s_cselect_b32 s13, s12, s13
	v_readlane_b32 s12, v244, 41
	s_cmp_eq_u32 s6, s12
	s_cbranch_scc1 .Lxb0_cend
	s_add_i32 s11, s11, 1
	s_cmp_lt_u32 s11, 0x40000
	s_cbranch_scc0 .Lxb0_cend
	s_sleep 1
	s_branch .Lxb0_cen
.Lxb0_cend:
	s_max_u32 s13, s13, 1
	s_max_u32 s7, s7, 1
	v_mov_b32_e32 v0, 0x23fc0
	v_mov_b32_e32 v2, s13
	v_mov_b32_e32 v3, s7
	ds_write_b32 v0, v2
	ds_write_b32 v0, v3 offset:4
	s_waitcnt lgkmcnt(0)
	v_mov_b32_e32 v0, 0x23fc0
	ds_read_b32 v2, v0
	ds_read_b32 v3, v0 offset:4
	s_getreg_b32 s12, hwreg(HW_REG_XCC_ID, 0, 4)
	s_and_b32 s12, s12, 15
	s_lshl_b32 s12, s12, 8
	s_add_i32 s10, s12, 0x1400
	s_add_i32 s12, s12, 0x2400
	v_mov_b32_e32 v5, s10
	v_mov_b32_e32 v6, s12
	global_atomic_add v7, v5, v1, s[92:93] sc0
	v_readlane_b32 s6, v244, 42
	s_add_i32 s6, s6, 1
	s_nop 0
	v_writelane_b32 v244, s6, 42
	s_waitcnt lgkmcnt(0)
	v_readfirstlane_b32 s10, v2
	v_readfirstlane_b32 s11, v3
	s_mul_i32 s10, s10, s6
	s_mul_i32 s11, s11, s6
	s_waitcnt vmcnt(0)
	v_readfirstlane_b32 s12, v7
	s_add_i32 s12, s12, 1
	s_cmp_eq_u32 s12, s10
	s_cbranch_scc0 .Lxb0_winv
	buffer_inv sc1
	buffer_wbl2 sc1
	s_waitcnt vmcnt(0)
	v_mov_b32_e32 v8, 0x3400
	global_atomic_add v7, v8, v1, s[92:93] sc0
	s_waitcnt vmcnt(0)
	v_readfirstlane_b32 s12, v7
	s_add_i32 s12, s12, 1
	s_cmp_eq_u32 s12, s11
	s_cbranch_scc0 .Lxb0_wait
	v_mov_b32_e32 v8, 0x2400
	global_atomic_add v8, v1, s[92:93]
	global_atomic_add v8, v1, s[92:93] offset:256
	global_atomic_add v8, v1, s[92:93] offset:512
	global_atomic_add v8, v1, s[92:93] offset:768
	global_atomic_add v8, v1, s[92:93] offset:1024
	global_atomic_add v8, v1, s[92:93] offset:1280
	global_atomic_add v8, v1, s[92:93] offset:1536
	global_atomic_add v8, v1, s[92:93] offset:1792
	global_atomic_add v8, v1, s[92:93] offset:2048
	global_atomic_add v8, v1, s[92:93] offset:2304
	global_atomic_add v8, v1, s[92:93] offset:2560
	global_atomic_add v8, v1, s[92:93] offset:2816
	global_atomic_add v8, v1, s[92:93] offset:3072
	global_atomic_add v8, v1, s[92:93] offset:3328
	global_atomic_add v8, v1, s[92:93] offset:3584
	global_atomic_add v8, v1, s[92:93] offset:3840
	s_branch .Lxb0_done

.Lxb0_done:
	s_waitcnt vmcnt(0)
	v_mov_b32_e32 v8, 0x5000
	global_load_dword v9, v8, s[92:93] sc1
	global_load_dword v10, v8, s[92:93] offset:256 sc1
	global_load_dword v11, v8, s[92:93] offset:512 sc1
	global_load_dword v12, v8, s[92:93] offset:768 sc1
	global_load_dword v13, v8, s[92:93] offset:1024 sc1
	global_load_dword v14, v8, s[92:93] offset:1280 sc1
	global_load_dword v15, v8, s[92:93] offset:1536 sc1
	global_load_dword v16, v8, s[92:93] offset:1792 sc1
	s_waitcnt vmcnt(0)
	v_mov_b32_e32 v2, 0
	v_add_u32_e32 v3, -1, v9
	v_and_b32_e32 v3, v3, v9
	v_or_b32_e32 v2, v2, v3
	v_add_u32_e32 v3, -1, v10
	v_and_b32_e32 v3, v3, v10
	v_or_b32_e32 v2, v2, v3
	v_add_u32_e32 v3, -1, v11
	v_and_b32_e32 v3, v3, v11
	v_or_b32_e32 v2, v2, v3
	v_add_u32_e32 v3, -1, v12
	v_and_b32_e32 v3, v3, v12
	v_or_b32_e32 v2, v2, v3
	v_add_u32_e32 v3, -1, v13
	v_and_b32_e32 v3, v3, v13
	v_or_b32_e32 v2, v2, v3
	v_add_u32_e32 v3, -1, v14
	v_and_b32_e32 v3, v3, v14
	v_or_b32_e32 v2, v2, v3
	v_add_u32_e32 v3, -1, v15
	v_and_b32_e32 v3, v3, v15
	v_or_b32_e32 v2, v2, v3
	v_add_u32_e32 v3, -1, v16
	v_and_b32_e32 v3, v3, v16
	v_or_b32_e32 v2, v2, v3
	s_nop 0
	v_readfirstlane_b32 s12, v2
	v_readlane_b32 s11, v244, 41
	s_cmp_eq_u32 s12, 0
	s_cselect_b32 s12, 1, 0
	s_cmp_eq_u32 s11, 0x100
	s_cselect_b32 s12, s12, 0
	s_nop 0
	v_writelane_b32 v244, s12, 43
	v_mov_b32_e32 v0, 0x23fc8
	v_mov_b32_e32 v2, s12
	ds_write_b32 v0, v2
	s_waitcnt lgkmcnt(0)

.LBB0_203:
	s_cmp_gt_i32 s95, 2
	v_readlane_b32 s34, v245, 7
	s_cselect_b64 s[0:1], -1, 0
	v_readlane_b32 s35, v245, 8
	s_and_b64 s[4:5], s[10:11], s[0:1]
	s_mul_i32 s8, s35, s34
	s_cmp_lt_u32 s14, 64
	s_cselect_b64 s[6:7], -1, 0
	s_mul_i32 s13, s8, s96
	s_add_u32 s8, s92, 0x200
	s_addc_u32 s9, s93, 0
	s_add_u32 s20, s92, 0x1000
	s_addc_u32 s21, s93, 0
	s_add_u32 s22, s92, 0x1100
	s_addc_u32 s23, s93, 0
	s_add_u32 s16, s92, 0x1200
	s_addc_u32 s17, s93, 0
	s_add_u32 s18, s92, 0x1300
	s_addc_u32 s19, s93, 0
	v_writelane_b32 v245, s8, 13
	s_cmp_eq_u32 s33, 15
	v_cndmask_b32_e64 v0, 0, 1, s[6:7]
	v_writelane_b32 v245, s9, 14
	s_cselect_b64 s[8:9], -1, 0
	v_writelane_b32 v245, s8, 15
	s_cmp_eq_u32 s33, 14
	s_nop 0
	v_writelane_b32 v245, s9, 16
	s_cselect_b64 s[8:9], -1, 0
	v_writelane_b32 v245, s8, 17
	s_cmp_eq_u32 s33, 13
	s_nop 0
	v_writelane_b32 v245, s9, 18
	s_cselect_b64 s[8:9], -1, 0
	v_writelane_b32 v245, s8, 19
	s_cmp_eq_u32 s33, 12
	s_nop 0
	v_writelane_b32 v245, s9, 20
	s_cselect_b64 s[8:9], -1, 0
	v_writelane_b32 v245, s8, 21
	s_cmp_eq_u32 s33, 11
	s_nop 0
	v_writelane_b32 v245, s9, 22
	s_cselect_b64 s[8:9], -1, 0
	v_writelane_b32 v245, s8, 23
	s_cmp_eq_u32 s33, 10
	s_nop 0
	v_writelane_b32 v245, s9, 24
	s_cselect_b64 s[8:9], -1, 0
	v_writelane_b32 v245, s8, 25
	s_cmp_eq_u32 s33, 9
	s_nop 0
	v_writelane_b32 v245, s9, 26
	s_cselect_b64 s[8:9], -1, 0
	v_writelane_b32 v245, s8, 27
	s_cmp_eq_u32 s33, 8
	s_nop 0
	v_writelane_b32 v245, s9, 28
	s_cselect_b64 s[8:9], -1, 0
	v_writelane_b32 v245, s8, 29
	s_cmp_eq_u32 s33, 7
	s_nop 0
	v_writelane_b32 v245, s9, 30
	s_cselect_b64 s[8:9], -1, 0
	v_writelane_b32 v245, s8, 31
	s_cmp_eq_u32 s33, 6
	s_nop 0
	v_writelane_b32 v245, s9, 32
	s_cselect_b64 s[8:9], -1, 0
	v_writelane_b32 v245, s8, 33
	s_cmp_eq_u32 s33, 5
	s_nop 0
	v_writelane_b32 v245, s9, 34
	s_cselect_b64 s[8:9], -1, 0
	v_writelane_b32 v245, s8, 35
	s_cmp_eq_u32 s33, 4
	s_nop 0
	v_writelane_b32 v245, s9, 36
	s_cselect_b64 s[8:9], -1, 0
	v_writelane_b32 v245, s8, 37
	s_cmp_eq_u32 s33, 3
	s_nop 0
	v_writelane_b32 v245, s9, 38
	s_cselect_b64 s[8:9], -1, 0
	v_writelane_b32 v245, s8, 39
	s_cmp_eq_u32 s33, 2
	s_nop 0
	v_writelane_b32 v245, s9, 40
	s_cselect_b64 s[8:9], -1, 0
	v_writelane_b32 v245, s8, 41
	s_cmp_eq_u32 s33, 1
	s_nop 0
	v_writelane_b32 v245, s9, 42
	s_cselect_b64 s[8:9], -1, 0
	v_writelane_b32 v245, s8, 43
	s_cmp_eq_u32 s33, 0
	s_nop 0
	v_writelane_b32 v245, s9, 44
	s_cselect_b64 s[8:9], -1, 0
	v_writelane_b32 v245, s8, 45
	s_nop 1
	v_writelane_b32 v245, s9, 46
	s_lshl_b32 s8, s33, 8
	s_add_u32 s8, s92, s8
	s_addc_u32 s9, s93, 0
	s_add_u32 s10, s8, 0x1400
	s_addc_u32 s11, s9, 0
	v_writelane_b32 v245, s10, 47
	s_add_u32 s8, s8, 0x2400
	s_addc_u32 s9, s9, 0
	v_writelane_b32 v245, s11, 48
	v_writelane_b32 v245, s8, 49
	s_nop 1
	v_writelane_b32 v245, s9, 50
	s_add_u32 s8, s92, 0x3400
	s_addc_u32 s9, s93, 0
	v_writelane_b32 v245, s8, 51
	s_nop 1
	v_writelane_b32 v245, s9, 52
	s_add_u32 s8, s92, 0x3500
	s_addc_u32 s9, s93, 0
	v_writelane_b32 v245, s8, 53
	s_andn2_b64 vcc, exec, s[4:5]
	v_cmp_ne_u32_e64 s[4:5], 1, v0
	v_writelane_b32 v245, s9, 54
	s_nop 0
	v_writelane_b32 v245, s4, 55
	s_nop 1
	v_writelane_b32 v245, s5, 56
	v_writelane_b32 v245, s13, 57
	v_writelane_b32 v245, s16, 58
	s_nop 1
	v_writelane_b32 v245, s17, 59
	v_writelane_b32 v245, s18, 60
	s_nop 1
	v_writelane_b32 v245, s19, 61
	s_cbranch_vccnz .LBB0_259
	s_waitcnt vmcnt(0)
	v_readlane_b32 s4, v245, 55
	v_readlane_b32 s5, v245, 56
	s_and_b64 vcc, exec, s[4:5]
	s_waitcnt vmcnt(0)
	s_barrier
	s_cbranch_vccnz .LBB0_258
	v_mbcnt_hi_u32_b32 v0, -1, v192
	v_cmp_eq_u32_e32 vcc, 0, v0
	s_and_saveexec_b64 s[4:5], vcc
	s_cbranch_execz .LBB0_257
	s_waitcnt vmcnt(0) lgkmcnt(0)
	v_mov_b32_e32 v1, 1
	v_readlane_b32 s11, v244, 43
	s_cmp_eq_u32 s11, 1
	s_cbranch_scc0 .Lxb1_glob
	s_and_b32 s12, s2, 7
	s_lshl_b32 s10, s12, 8
	s_add_i32 s10, s10, 0x6000
	v_mov_b32_e32 v6, s10
	global_atomic_add v6, v1, s[92:93]
	buffer_inv sc1
	v_readlane_b32 s11, v244, 41
	s_sub_i32 s11, s11, s12
	s_add_i32 s11, s11, 7
	s_lshr_b32 s11, s11, 3
	s_mul_i32 s6, s11, 1
	s_branch .Lxb1_wait

.LBB0_259:
	s_cmp_lt_i32 s94, 3
	s_cselect_b64 s[36:37], -1, 0
	s_and_b64 s[0:1], s[36:37], s[0:1]
	s_andn2_b64 vcc, exec, s[0:1]
	v_writelane_b32 v245, s20, 62
	v_writelane_b32 v244, s22, 0
	s_nop 0
	v_writelane_b32 v245, s21, 63
	v_writelane_b32 v244, s23, 1
	s_cbranch_vccnz .LBB0_495
	v_mov_b32_e32 v46, 0x23fc8
	ds_read_b32 v46, v46
	s_movk_i32 s4, 0x800
	v_readlane_b32 s5, v244, 41
	s_waitcnt lgkmcnt(0)
	v_readfirstlane_b32 s0, v46
	s_cmp_eq_u32 s0, 1
	s_cbranch_scc0 .Lg1_set
	s_and_b32 s4, s2, 7
	s_lshl_b32 s4, s4, 8
	s_lshr_b32 s2, s2, 3
	s_add_i32 s2, s2, s4
	s_addk_i32 s4, 0x100
	s_mov_b32 s5, 32
.Lg1_set:
	v_writelane_b32 v244, s5, 45
	v_writelane_b32 v244, s4, 46
	s_cmpk_lt_i32 s2, 0x800
	v_mbcnt_hi_u32_b32 v46, -1, v192
	v_readlane_b32 s4, v245, 0
	s_cselect_b64 s[0:1], -1, 0
	s_lshl_b64 s[10:11], s[2:3], 14
	v_add_u32_e32 v193, s4, v46
	s_cmpk_gt_i32 s2, 0x7ff
	s_nop 0
	v_readfirstlane_b32 s14, v193
	s_cbranch_scc1 .LBB0_282
	v_ashrrev_i32_e32 v44, 7, v193
	v_cmp_gt_i32_e32 vcc, 3, v44
	s_and_saveexec_b64 s[4:5], vcc
	s_cbranch_execz .LBB0_281
	v_mov_b32_e32 v0, 0xad00000
	v_mov_b32_e32 v1, 0x8d00000
	v_cmp_eq_u32_e32 vcc, 1, v44
	s_movk_i32 s13, 0x7f
	s_add_u32 s8, s92, s10
	v_cndmask_b32_e32 v0, v0, v1, vcc
	v_mov_b32_e32 v1, 0x6d00000
	v_cmp_lt_u32_e32 vcc, s13, v193
	s_addc_u32 s9, s93, s11
	s_add_i32 s12, s2, -8
	v_cndmask_b32_e32 v4, v1, v0, vcc
	v_mov_b32_e32 v5, 0
	v_ashrrev_i32_e32 v45, 31, v44
	v_lshl_add_u64 v[0:1], s[8:9], 0, v[4:5]
	v_mad_i64_i32 v[2:3], s[8:9], s12, 3, v[44:45]
	s_movk_i32 s12, 0x300
	v_mov_b64_e32 v[6:7], s[30:31]
	v_mad_u64_u32 v[6:7], s[8:9], v2, s12, v[6:7]
	s_and_b32 s6, s2, 0xf8
	v_mad_i32_i24 v7, v3, s12, v7
	v_lshrrev_b32_e32 v2, 1, v193
	v_lshlrev_b32_e32 v3, 4, v193
	s_cmp_lg_u32 s6, 0
	v_and_b32_e32 v2, 56, v2
	v_and_b32_e32 v4, 0xf0, v3
	s_cselect_b64 s[6:7], -1, 0
	v_lshl_add_u64 v[12:13], v[0:1], 0, v[4:5]
	v_cmp_ne_u32_e64 s[40:41], 0, v2
	v_lshlrev_b32_e32 v14, 8, v2
	s_and_saveexec_b64 s[8:9], s[40:41]
	s_xor_b64 s[8:9], exec, s[8:9]
	s_cbranch_execz .LBB0_264
	v_mov_b32_e32 v15, v5
	v_lshl_add_u64 v[0:1], v[12:13], 0, v[14:15]
	global_load_dwordx4 v[0:3], v[0:1], off offset:-768

.LBB0_282:
	s_andn2_b64 vcc, exec, s[0:1]
	s_cbranch_vccnz .LBB0_495
	s_ashr_i32 s0, s14, 6
	v_writelane_b32 v244, s36, 2
	s_add_u32 s4, s92, 0x180000
	s_addc_u32 s5, s93, 0
	v_writelane_b32 v244, s37, 3
	v_writelane_b32 v244, s4, 4
	v_and_b32_e32 v44, 64, v46
	v_add_u32_e32 v45, -1, v46
	v_writelane_b32 v244, s5, 5
	s_add_u32 s4, s92, 0x100000
	s_addc_u32 s5, s93, 0
	v_writelane_b32 v244, s4, 6
	s_cmp_eq_u32 s0, 7
	v_cmp_lt_i32_e32 vcc, v45, v44
	v_writelane_b32 v244, s5, 7
	s_cselect_b64 s[4:5], -1, 0
	s_and_b32 s1, s0, 3
	v_writelane_b32 v244, s4, 8
	s_cmp_gt_u32 s0, 3
	v_cndmask_b32_e32 v45, v45, v46, vcc
	v_writelane_b32 v244, s5, 9
	s_cselect_b64 s[64:65], -1, 0
	s_add_i32 s4, 0, 0x4000
	v_lshlrev_b32_e32 v194, 2, v45
	v_add_u32_e32 v45, -2, v46
	s_cmp_lt_u32 s0, 4
	v_cmp_lt_i32_e32 vcc, v45, v44
	v_writelane_b32 v244, s4, 10
	s_cselect_b32 s29, s4, 0
	s_lshl_b32 s4, s1, 8
	v_cndmask_b32_e32 v45, v45, v46, vcc
	s_cmp_eq_u32 s1, 0
	v_lshlrev_b32_e32 v195, 2, v45
	v_add_u32_e32 v45, -4, v46
	s_cselect_b64 s[68:69], -1, 0
	s_cmp_lg_u32 s1, 0
	v_cmp_lt_i32_e32 vcc, v45, v44
	s_cselect_b64 s[70:71], -1, 0
	s_cmp_lt_u32 s1, 2
	v_cndmask_b32_e32 v45, v45, v46, vcc
	s_cselect_b64 s[72:73], -1, 0
	s_cmp_gt_u32 s1, 1
	v_lshlrev_b32_e32 v196, 2, v45
	v_add_u32_e32 v45, -8, v46
	s_cselect_b64 s[86:87], -1, 0
	s_cmp_lg_u32 s1, 3
	v_cmp_lt_i32_e32 vcc, v45, v44
	s_cselect_b64 s[6:7], -1, 0
	s_cmp_eq_u32 s1, 3
	v_cndmask_b32_e32 v45, v45, v46, vcc
	v_writelane_b32 v244, s4, 11
	s_cselect_b64 s[4:5], -1, 0
	s_lshl_b32 s8, s1, 4
	v_lshlrev_b32_e32 v197, 2, v45
	v_add_u32_e32 v45, -16, v46
	v_writelane_b32 v244, s8, 13
	s_lshl_b32 s8, s1, 6
	v_cmp_lt_i32_e32 vcc, v45, v44
	s_add_i32 s8, s8, 0
	s_add_i32 s9, s8, 0x1f400
	v_cndmask_b32_e32 v45, v45, v46, vcc
	s_add_i32 s8, s8, 0x1f600
	v_lshlrev_b32_e32 v198, 2, v45
	v_subrev_u32_e32 v45, 32, v46
	v_writelane_b32 v244, s9, 15
	s_cmp_eq_u32 s1, 1
	v_cmp_lt_i32_e32 vcc, v45, v44
	v_writelane_b32 v244, s8, 16
	s_cselect_b64 s[8:9], -1, 0
	v_cndmask_b32_e32 v45, v45, v46, vcc
	v_writelane_b32 v244, s8, 17
	s_cmp_eq_u32 s1, 2
	v_lshlrev_b32_e32 v199, 2, v45
	v_bfrev_b32_e32 v45, 0.5
	v_writelane_b32 v244, s9, 18
	s_cselect_b64 s[8:9], -1, 0
	s_cmp_lt_i32 s0, 4
	v_lshl_or_b32 v200, v46, 2, v45
	v_xor_b32_e32 v45, 1, v46
	v_add_u32_e32 v44, 64, v44
	s_cselect_b64 s[12:13], -1, 0
	s_lshl_b32 s1, s0, 12
	v_cmp_lt_i32_e32 vcc, v45, v44
	s_add_i32 s1, s1, 0
	s_andn2_b32 s14, s14, 63
	v_cndmask_b32_e32 v45, v46, v45, vcc
	v_writelane_b32 v244, s8, 19
	s_add_i32 s1, s1, s14
	v_lshlrev_b32_e32 v201, 2, v45
	v_xor_b32_e32 v45, 2, v46
	v_writelane_b32 v244, s9, 20
	s_add_i32 s1, s1, 0x19000
	v_cmp_lt_i32_e32 vcc, v45, v44
	v_writelane_b32 v244, s1, 21
	s_lshl_b32 s1, s0, 9
	v_cndmask_b32_e32 v45, v46, v45, vcc
	s_add_i32 s1, s1, 0
	v_lshlrev_b32_e32 v202, 2, v45
	v_xor_b32_e32 v45, 4, v46
	s_add_i32 s1, s1, 0x21c00
	v_cmp_lt_i32_e32 vcc, v45, v44
	v_writelane_b32 v244, s1, 22
	s_lshl_b32 s1, s0, 5
	v_cndmask_b32_e32 v45, v46, v45, vcc
	s_add_i32 s21, s1, 0
	s_lshl_b32 s23, s0, 8
	s_lshl_b64 s[0:1], s[2:3], 2
	v_lshlrev_b32_e32 v203, 2, v45
	v_xor_b32_e32 v45, 8, v46
	s_add_u32 s34, s0, 0x80000
	v_cmp_lt_i32_e32 vcc, v45, v44
	s_addc_u32 s35, s1, 0
	s_lshl_b64 s[78:79], s[84:85], 2
	s_lshl_b64 s[0:1], s[2:3], 13
	v_cndmask_b32_e32 v44, v46, v45, vcc
	s_add_u32 s36, s0, 0xcd00000
	v_lshlrev_b32_e32 v204, 2, v44
	s_mov_b32 s67, 0
	s_addc_u32 s37, s1, 0
	s_lshl_b64 s[16:17], s[84:85], 13
	s_lshl_b64 s[18:19], s[84:85], 14
	s_lshl_b32 s22, s2, 3
	v_mov_b32_e32 v45, 0
	s_movk_i32 s50, 0x210
	s_add_i32 s51, 0, 0x10400
	s_movk_i32 s33, 0x110
	s_add_i32 s14, 0, 0x14800
	s_add_i32 s15, 0, 0x1d000
	s_add_i32 s20, 0, 0x1f800
	s_movk_i32 s0, 0x90
	s_mov_b32 s1, 0xdd00000
	s_mov_b32 s96, 0xffffff0
	v_mov_b32_e32 v205, 0x3db504f3
	v_mov_b32_e32 v206, 0x100
	v_mov_b32_e32 v207, 0xad00000
	v_mov_b32_e32 v208, 0x8d00000
	v_mov_b32_e32 v209, 0x6d00000
	v_readlane_b32 s38, v244, 45
	s_cmp_eq_u32 s38, 32
	s_cbranch_scc0 .Lg1_nostr
	s_mov_b64 s[78:79], 0x80
	s_mov_b64 s[16:17], 0x40000
	s_mov_b64 s[18:19], 0x80000
	s_movk_i32 s28, 0x100
.Lg1_nostr:
	s_mov_b32 s97, s2
	v_ashrrev_i32_e32 v217, 7, v193
	v_and_b32_e32 v242, 15, v193
	s_and_b32 s38, s2, 7
	s_lshl_b32 s38, s38, 9
	v_cmp_gt_i32_e32 vcc, 3, v217
	s_and_saveexec_b64 s[40:41], vcc
	v_lshlrev_b32_e32 v217, 12, v217
	v_lshl_add_u32 v217, v242, 5, v217
	v_add_u32_e32 v217, s38, v217
	global_load_dwordx4 v[218:221], v217, s[82:83]
	global_load_dwordx4 v[222:225], v217, s[82:83] offset:16
	v_add_u32_e32 v242, 0x3000, v217
	global_load_dwordx4 v[226:229], v242, s[82:83]
	global_load_dwordx4 v[230:233], v242, s[82:83] offset:16
	v_add_u32_e32 v242, 0x6000, v217
	global_load_dwordx4 v[234:237], v242, s[82:83]
	global_load_dwordx4 v[238:241], v242, s[82:83] offset:16
	v_add_u32_e32 v242, 0x9000, v217
	global_load_dwordx4 v[248:251], v242, s[82:83]
	global_load_dwordx4 v[252:255], v242, s[82:83] offset:16
	s_or_b64 exec, exec, s[40:41]
	s_waitcnt vmcnt(0)
	s_branch .LBB0_286

.LBB0_359:
	s_or_b64 exec, exec, s[8:9]
	v_readlane_b32 s8, v244, 45
	s_add_i32 s97, s97, s8
	v_readlane_b32 s66, v244, 46
	s_cmp_ge_i32 s97, s66
	s_cselect_b64 s[8:9], -1, 0
	s_cmp_lt_i32 s97, s66
	s_cselect_b32 s66, s97, -1
	s_cmp_gt_i32 s66, -1
	s_cselect_b64 s[38:39], -1, 0
	s_xor_b64 s[40:41], vcc, -1
	s_and_b64 s[38:39], s[38:39], s[40:41]
	v_lshrrev_b32_e32 v213, 1, v210
	v_lshlrev_b32_e32 v190, 4, v210
	s_waitcnt lgkmcnt(0)
	s_barrier
	s_and_saveexec_b64 s[42:43], s[38:39]
	s_cbranch_execz .LBB0_379
	v_cmp_eq_u32_e32 vcc, 1, v188
	s_movk_i32 s38, 0x7f
	v_and_b32_e32 v2, 56, v213
	v_cndmask_b32_e32 v0, v207, v208, vcc
	v_cmp_lt_u32_e32 vcc, s38, v210
	s_lshl_b64 s[38:39], s[66:67], 14
	v_lshlrev_b32_e32 v14, 8, v2
	v_cndmask_b32_e32 v44, v209, v0, vcc
	v_lshl_add_u64 v[0:1], s[92:93], 0, v[44:45]
	v_lshl_add_u64 v[0:1], v[0:1], 0, s[38:39]
	s_and_b32 s38, s66, 0xf8
	s_cmp_lg_u32 s38, 0
	v_and_b32_e32 v44, 0xf0, v190
	s_cselect_b64 s[40:41], -1, 0
	v_lshl_add_u64 v[12:13], v[0:1], 0, v[44:45]
	v_cmp_ne_u32_e64 s[38:39], 0, v2
	s_and_saveexec_b64 s[44:45], s[38:39]
	s_xor_b64 s[44:45], exec, s[44:45]
	s_cbranch_execz .LBB0_362
	v_mov_b32_e32 v15, v45
	v_lshl_add_u64 v[0:1], v[12:13], 0, v[14:15]
	global_load_dwordx4 v[0:3], v[0:1], off offset:-768

.LBB0_495:
	v_readlane_b32 s2, v244, 44
	s_cmp_gt_i32 s95, 3
	s_cselect_b64 s[4:5], -1, 0
	s_and_b64 s[0:1], s[36:37], s[4:5]
	s_andn2_b64 vcc, exec, s[0:1]
	s_cbranch_vccnz .LBB0_551
	s_waitcnt vmcnt(0)
	v_readlane_b32 s0, v245, 55
	v_readlane_b32 s1, v245, 56
	s_and_b64 vcc, exec, s[0:1]
	s_waitcnt vmcnt(0)
	s_barrier
	s_cbranch_vccnz .LBB0_550
	v_mbcnt_hi_u32_b32 v0, -1, v192
	v_cmp_eq_u32_e32 vcc, 0, v0
	s_and_saveexec_b64 s[0:1], vcc
	v_readlane_b32 s13, v245, 57
	s_cbranch_execz .LBB0_549
	s_waitcnt vmcnt(0) lgkmcnt(0)
	v_mov_b32_e32 v1, 1
	v_readlane_b32 s11, v244, 43
	s_cmp_eq_u32 s11, 1
	s_cbranch_scc0 .Lxb2_glob
	s_and_b32 s12, s2, 7
	s_lshl_b32 s10, s12, 8
	s_add_i32 s10, s10, 0x6000
	v_mov_b32_e32 v6, s10
	global_atomic_add v6, v1, s[92:93]
	buffer_inv sc1
	v_readlane_b32 s11, v244, 41
	s_sub_i32 s11, s11, s12
	s_add_i32 s11, s11, 7
	s_lshr_b32 s11, s11, 3
	s_mul_i32 s6, s11, 2
	s_branch .Lxb2_wait

.LBB0_684:
	s_cmp_gt_i32 s95, 5
	s_cselect_b64 s[0:1], -1, 0
	s_and_b64 s[4:5], s[40:41], s[0:1]
	v_readlane_b32 s64, v245, 53
	s_andn2_b64 vcc, exec, s[4:5]
	v_readlane_b32 s65, v245, 54
	s_cbranch_vccnz .LBB0_740
	s_waitcnt vmcnt(0)
	v_readlane_b32 s4, v245, 55
	v_readlane_b32 s5, v245, 56
	s_and_b64 vcc, exec, s[4:5]
	s_waitcnt vmcnt(0)
	s_barrier
	s_cbranch_vccnz .LBB0_739
	v_mbcnt_hi_u32_b32 v0, -1, v192
	v_cmp_eq_u32_e32 vcc, 0, v0
	s_and_saveexec_b64 s[4:5], vcc
	s_cbranch_execz .LBB0_738
	s_waitcnt vmcnt(0) lgkmcnt(0)
	v_mov_b32_e32 v1, 1
	v_readlane_b32 s11, v244, 43
	s_cmp_eq_u32 s11, 1
	s_cbranch_scc0 .Lxb4_glob
	s_and_b32 s12, s2, 7
	s_lshl_b32 s10, s12, 8
	s_add_i32 s10, s10, 0x6000
	v_mov_b32_e32 v6, s10
	global_atomic_add v6, v1, s[92:93]
	buffer_inv sc1
	v_readlane_b32 s11, v244, 41
	s_sub_i32 s11, s11, s12
	s_add_i32 s11, s11, 7
	s_lshr_b32 s11, s11, 3
	s_mul_i32 s6, s11, 3
	s_branch .Lxb4_wait

.LBB0_908:
	s_cmp_gt_i32 s95, 7
	s_cselect_b64 s[4:5], -1, 0
	s_and_b64 s[0:1], s[0:1], s[4:5]
	s_andn2_b64 vcc, exec, s[0:1]
	s_cbranch_vccnz .LBB0_964
	s_waitcnt vmcnt(0)
	v_readlane_b32 s0, v245, 55
	v_readlane_b32 s1, v245, 56
	s_and_b64 vcc, exec, s[0:1]
	s_waitcnt lgkmcnt(0)
	s_barrier
	s_cbranch_vccnz .LBB0_963
	v_mbcnt_hi_u32_b32 v0, -1, v192
	v_cmp_eq_u32_e32 vcc, 0, v0
	s_and_saveexec_b64 s[0:1], vcc
	s_cbranch_execz .LBB0_962
	s_waitcnt vmcnt(0) lgkmcnt(0)
	v_mov_b32_e32 v1, 1
	v_readlane_b32 s11, v244, 43
	s_cmp_eq_u32 s11, 1
	s_cbranch_scc0 .Lxb6_glob
	s_and_b32 s12, s2, 7
	s_lshl_b32 s10, s12, 8
	s_add_i32 s10, s10, 0x6000
	v_mov_b32_e32 v6, s10
	global_atomic_add v6, v1, s[92:93]
	buffer_inv sc1
	v_readlane_b32 s11, v244, 41
	s_sub_i32 s11, s11, s12
	s_add_i32 s11, s11, 7
	s_lshr_b32 s11, s11, 3
	s_mul_i32 s6, s11, 4
	s_branch .Lxb6_wait

.LBB0_981:
	s_cmp_gt_i32 s95, 8
	s_cselect_b64 s[4:5], -1, 0
	s_and_b64 s[0:1], s[0:1], s[4:5]
	s_andn2_b64 vcc, exec, s[0:1]
	s_cbranch_vccnz .LBB0_1037
	s_waitcnt vmcnt(0)
	v_readlane_b32 s0, v245, 55
	v_readlane_b32 s1, v245, 56
	s_and_b64 vcc, exec, s[0:1]
	s_waitcnt lgkmcnt(0)
	s_barrier
	s_cbranch_vccnz .LBB0_1036
	v_mbcnt_hi_u32_b32 v0, -1, v192
	v_cmp_eq_u32_e32 vcc, 0, v0
	s_and_saveexec_b64 s[0:1], vcc
	s_cbranch_execz .LBB0_1035
	s_waitcnt vmcnt(0) lgkmcnt(0)
	v_mov_b32_e32 v1, 1
	v_readlane_b32 s11, v244, 43
	s_cmp_eq_u32 s11, 1
	s_cbranch_scc0 .Lxb7_glob
	s_and_b32 s12, s2, 7
	s_lshl_b32 s10, s12, 8
	s_add_i32 s10, s10, 0x6000
	v_mov_b32_e32 v6, s10
	global_atomic_add v6, v1, s[92:93]
	buffer_inv sc1
	v_readlane_b32 s11, v244, 41
	s_sub_i32 s11, s11, s12
	s_add_i32 s11, s11, 7
	s_lshr_b32 s11, s11, 3
	s_mul_i32 s6, s11, 5
	s_branch .Lxb7_wait
